# GEMM tile prologues: the 128-register accumulator zeroing uses 64-bit moves (v_mov_b64 v[n:n+1], 0), half the instructions
# speedup vs baseline: 1.0085x; 1.0027x over previous
; template <class Sched, class Epi>
; DI void gemm_stream(char* smem, const Sched& S_, const Epi& E) {
;     ...
;     const bool has_next = S_.next(ui + 1, nxt);
;     if (!has_next) nxt = cur;
;     const char* nA = nxt.A; const char* nB = nxt.B;
;     const int nt = cur.nt;
;     const int la2 = cur.lda * 2; const size_t hA = (size_t)HALF * la2;
;     for (int t = 0; t < nt; t += 2) {
;       const bool last = (t == nt - 2);
;       const char* a1 = cA + (size_t)(t + 1) * kstep;
;       const char* a2 = last ? nA : cA + (size_t)(t + 2) * kstep; const char* b2 = last ? nB : cB + (size_t)(t + 2) * kstep;
;       const char* a3 = a2 + kstep; const char* b3 = b2 + kstep;
;       const int xa2 = (last ? nxt.lda : cur.lda) * 2, xb2 = (last ? nxt.ldb : cur.ldb) * 2;
;       const size_t xhA = (size_t)HALF * xa2, xhB = (size_t)HALF * xb2;
;     ...
; #pragma unroll
;     for (int a = 0; a < 2; ++a)
; #pragma unroll
;       for (int b = 0; b < 2; ++b)
; #pragma unroll
;         for (int m = 0; m < 4; ++m)
; #pragma unroll
;           for (int n = 0; n < 2; ++n) acc[a][b][m][n] = (f32x4){0.f, 0.f, 0.f, 0.f};
;     cur = nxt; cA = nA; cB = nB; ++ui;
.LBB0_465:
	s_add_u32 s44, s44, 0x40080
	s_addc_u32 s45, s45, 0
	s_add_u32 s1, s46, 0x100
	v_mov_b32_e32 v0, 0
	s_addc_u32 s27, s47, 0
	s_mov_b32 s49, -2
	v_mov_b32_e32 v1, 0
	v_mov_b64_e32 v[2:3], 0
	v_mov_b64_e32 v[4:5], 0
	v_mov_b64_e32 v[6:7], 0
	v_mov_b64_e32 v[8:9], 0
	v_mov_b64_e32 v[10:11], 0
	v_mov_b64_e32 v[12:13], 0
	v_mov_b64_e32 v[14:15], 0
	v_mov_b64_e32 v[16:17], 0
	v_mov_b64_e32 v[18:19], 0
	v_mov_b64_e32 v[24:25], 0
	v_mov_b64_e32 v[26:27], 0
	v_mov_b64_e32 v[32:33], 0
	v_mov_b64_e32 v[34:35], 0
	v_mov_b64_e32 v[40:41], 0
	v_mov_b64_e32 v[42:43], 0
	v_mov_b64_e32 v[20:21], 0
	v_mov_b64_e32 v[22:23], 0
	v_mov_b64_e32 v[28:29], 0
	v_mov_b64_e32 v[30:31], 0
	v_mov_b64_e32 v[36:37], 0
	v_mov_b64_e32 v[38:39], 0
	v_mov_b64_e32 v[44:45], 0
	v_mov_b64_e32 v[46:47], 0
	v_mov_b64_e32 v[48:49], 0
	v_mov_b64_e32 v[50:51], 0
	v_mov_b64_e32 v[52:53], 0
	v_mov_b64_e32 v[54:55], 0
	v_mov_b64_e32 v[56:57], 0
	v_mov_b64_e32 v[58:59], 0
	v_mov_b64_e32 v[60:61], 0
	v_mov_b64_e32 v[62:63], 0
	v_mov_b64_e32 v[64:65], 0
	v_mov_b64_e32 v[66:67], 0
	v_mov_b64_e32 v[68:69], 0
	v_mov_b64_e32 v[70:71], 0
	v_mov_b64_e32 v[72:73], 0
	v_mov_b64_e32 v[74:75], 0
	v_mov_b64_e32 v[76:77], 0
	v_mov_b64_e32 v[78:79], 0
	v_mov_b64_e32 v[80:81], 0
	v_mov_b64_e32 v[82:83], 0
	v_mov_b64_e32 v[88:89], 0
	v_mov_b64_e32 v[90:91], 0
	v_mov_b64_e32 v[96:97], 0
	v_mov_b64_e32 v[98:99], 0
	v_mov_b64_e32 v[104:105], 0
	v_mov_b64_e32 v[106:107], 0
	v_mov_b64_e32 v[84:85], 0
	v_mov_b64_e32 v[86:87], 0
	v_mov_b64_e32 v[92:93], 0
	v_mov_b64_e32 v[94:95], 0
	v_mov_b64_e32 v[100:101], 0
	v_mov_b64_e32 v[102:103], 0
	v_mov_b64_e32 v[108:109], 0
	v_mov_b64_e32 v[110:111], 0
	v_mov_b64_e32 v[112:113], 0
	v_mov_b64_e32 v[114:115], 0
	v_mov_b64_e32 v[116:117], 0
	v_mov_b64_e32 v[118:119], 0
	v_mov_b64_e32 v[120:121], 0
	v_mov_b64_e32 v[122:123], 0
	v_mov_b64_e32 v[124:125], 0
	v_mov_b64_e32 v[126:127], 0

; template <class Sched, class Epi>
; DI void gemm_stream(char* smem, const Sched& S_, const Epi& E) {
;     ...
;     const bool has_next = S_.next(ui + 1, nxt);
;     if (!has_next) nxt = cur;
;     const char* nA = nxt.A; const char* nB = nxt.B;
;     const int nt = cur.nt;
;     const int la2 = cur.lda * 2; const size_t hA = (size_t)HALF * la2;
;     for (int t = 0; t < nt; t += 2) {
;       const bool last = (t == nt - 2);
;       const char* a1 = cA + (size_t)(t + 1) * kstep;
;       const char* a2 = last ? nA : cA + (size_t)(t + 2) * kstep; const char* b2 = last ? nB : cB + (size_t)(t + 2) * kstep;
;       const char* a3 = a2 + kstep; const char* b3 = b2 + kstep;
;       const int xa2 = (last ? nxt.lda : cur.lda) * 2, xb2 = (last ? nxt.ldb : cur.ldb) * 2;
;       const size_t xhA = (size_t)HALF * xa2, xhB = (size_t)HALF * xb2;
;     ...
; #pragma unroll
;     for (int a = 0; a < 2; ++a)
; #pragma unroll
;       for (int b = 0; b < 2; ++b)
; #pragma unroll
;         for (int m = 0; m < 4; ++m)
; #pragma unroll
;           for (int n = 0; n < 2; ++n) acc[a][b][m][n] = (f32x4){0.f, 0.f, 0.f, 0.f};
;     cur = nxt; cA = nA; cB = nB; ++ui;
.LBB0_653:
	s_lshl_b32 s44, s62, 1
	s_ashr_i32 s45, s44, 31
	s_lshl_b64 s[46:47], s[44:45], 7
	s_add_i32 s63, s5, -2
	s_add_u32 s36, s36, 0x80
	s_addc_u32 s37, s37, 0
	s_add_u32 vcc_lo, s40, 0x100
	s_addc_u32 vcc_hi, s41, 0
	v_mad_u64_u32 v[0:1], s[40:41], s44, v129, v[134:135]
	v_mov_b32_e32 v1, v221
	v_lshl_add_u64 v[138:139], s[46:47], 0, v[0:1]
	v_mad_u64_u32 v[0:1], s[40:41], s44, v131, v[136:137]
	v_mov_b32_e32 v1, v221
	v_lshl_add_u64 v[140:141], s[46:47], 0, v[0:1]
	v_mov_b32_e32 v0, 0
	s_mov_b32 s40, 0
	v_mov_b32_e32 v1, 0
	v_mov_b64_e32 v[2:3], 0
	v_mov_b64_e32 v[4:5], 0
	v_mov_b64_e32 v[6:7], 0
	v_mov_b64_e32 v[8:9], 0
	v_mov_b64_e32 v[10:11], 0
	v_mov_b64_e32 v[12:13], 0
	v_mov_b64_e32 v[14:15], 0
	v_mov_b64_e32 v[16:17], 0
	v_mov_b64_e32 v[18:19], 0
	v_mov_b64_e32 v[20:21], 0
	v_mov_b64_e32 v[22:23], 0
	v_mov_b64_e32 v[28:29], 0
	v_mov_b64_e32 v[30:31], 0
	v_mov_b64_e32 v[36:37], 0
	v_mov_b64_e32 v[38:39], 0
	v_mov_b64_e32 v[24:25], 0
	v_mov_b64_e32 v[26:27], 0
	v_mov_b64_e32 v[32:33], 0
	v_mov_b64_e32 v[34:35], 0
	v_mov_b64_e32 v[40:41], 0
	v_mov_b64_e32 v[42:43], 0
	v_mov_b64_e32 v[44:45], 0
	v_mov_b64_e32 v[46:47], 0
	v_mov_b64_e32 v[48:49], 0
	v_mov_b64_e32 v[50:51], 0
	v_mov_b64_e32 v[52:53], 0
	v_mov_b64_e32 v[54:55], 0
	v_mov_b64_e32 v[56:57], 0
	v_mov_b64_e32 v[58:59], 0
	v_mov_b64_e32 v[60:61], 0
	v_mov_b64_e32 v[62:63], 0
	v_mov_b64_e32 v[64:65], 0
	v_mov_b64_e32 v[66:67], 0
	v_mov_b64_e32 v[68:69], 0
	v_mov_b64_e32 v[70:71], 0
	v_mov_b64_e32 v[72:73], 0
	v_mov_b64_e32 v[74:75], 0
	v_mov_b64_e32 v[76:77], 0
	v_mov_b64_e32 v[78:79], 0
	v_mov_b64_e32 v[80:81], 0
	v_mov_b64_e32 v[82:83], 0
	v_mov_b64_e32 v[84:85], 0
	v_mov_b64_e32 v[86:87], 0
	v_mov_b64_e32 v[88:89], 0
	v_mov_b64_e32 v[90:91], 0
	v_mov_b64_e32 v[96:97], 0
	v_mov_b64_e32 v[98:99], 0
	v_mov_b64_e32 v[92:93], 0
	v_mov_b64_e32 v[94:95], 0
	v_mov_b64_e32 v[100:101], 0
	v_mov_b64_e32 v[102:103], 0
	v_mov_b64_e32 v[104:105], 0
	v_mov_b64_e32 v[106:107], 0
	v_mov_b64_e32 v[108:109], 0
	v_mov_b64_e32 v[110:111], 0
	v_mov_b64_e32 v[112:113], 0
	v_mov_b64_e32 v[114:115], 0
	v_mov_b64_e32 v[116:117], 0
	v_mov_b64_e32 v[118:119], 0
	v_mov_b64_e32 v[120:121], 0
	v_mov_b64_e32 v[122:123], 0
	v_mov_b64_e32 v[124:125], 0
	v_mov_b64_e32 v[126:127], 0

; template <class Sched, class Epi>
; DI void gemm_stream(char* smem, const Sched& S_, const Epi& E) {
;     ...
;     const bool has_next = S_.next(ui + 1, nxt);
;     if (!has_next) nxt = cur;
;     const char* nA = nxt.A; const char* nB = nxt.B;
;     const int nt = cur.nt;
;     const int la2 = cur.lda * 2; const size_t hA = (size_t)HALF * la2;
;     for (int t = 0; t < nt; t += 2) {
;       const bool last = (t == nt - 2);
;       const char* a1 = cA + (size_t)(t + 1) * kstep;
;       const char* a2 = last ? nA : cA + (size_t)(t + 2) * kstep; const char* b2 = last ? nB : cB + (size_t)(t + 2) * kstep;
;       const char* a3 = a2 + kstep; const char* b3 = b2 + kstep;
;       const int xa2 = (last ? nxt.lda : cur.lda) * 2, xb2 = (last ? nxt.ldb : cur.ldb) * 2;
;       const size_t xhA = (size_t)HALF * xa2, xhB = (size_t)HALF * xb2;
;     ...
; #pragma unroll
;     for (int a = 0; a < 2; ++a)
; #pragma unroll
;       for (int b = 0; b < 2; ++b)
; #pragma unroll
;         for (int m = 0; m < 4; ++m)
; #pragma unroll
;           for (int n = 0; n < 2; ++n) acc[a][b][m][n] = (f32x4){0.f, 0.f, 0.f, 0.f};
;     cur = nxt; cA = nA; cB = nB; ++ui;
.LBB0_932:
	s_lshl_b32 s42, s20, 1
	s_ashr_i32 s43, s42, 31
	s_lshl_b64 s[44:45], s[42:43], 7
	s_add_i32 vcc_lo, s5, -2
	s_add_u32 s36, s36, 0x80
	s_addc_u32 s37, s37, 0
	s_add_u32 vcc_hi, s40, 0x100
	s_addc_u32 s52, s41, 0
	v_mad_u64_u32 v[0:1], s[40:41], s42, v129, v[134:135]
	v_mov_b32_e32 v1, v221
	v_lshl_add_u64 v[138:139], s[44:45], 0, v[0:1]
	v_mad_u64_u32 v[0:1], s[40:41], s42, v131, v[136:137]
	v_mov_b32_e32 v1, v221
	v_lshl_add_u64 v[140:141], s[44:45], 0, v[0:1]
	v_mov_b32_e32 v0, 0
	s_mov_b32 s40, 0
	v_mov_b32_e32 v1, 0
	v_mov_b64_e32 v[2:3], 0
	v_mov_b64_e32 v[4:5], 0
	v_mov_b64_e32 v[6:7], 0
	v_mov_b64_e32 v[8:9], 0
	v_mov_b64_e32 v[10:11], 0
	v_mov_b64_e32 v[12:13], 0
	v_mov_b64_e32 v[14:15], 0
	v_mov_b64_e32 v[16:17], 0
	v_mov_b64_e32 v[18:19], 0
	v_mov_b64_e32 v[20:21], 0
	v_mov_b64_e32 v[22:23], 0
	v_mov_b64_e32 v[28:29], 0
	v_mov_b64_e32 v[30:31], 0
	v_mov_b64_e32 v[36:37], 0
	v_mov_b64_e32 v[38:39], 0
	v_mov_b64_e32 v[24:25], 0
	v_mov_b64_e32 v[26:27], 0
	v_mov_b64_e32 v[32:33], 0
	v_mov_b64_e32 v[34:35], 0
	v_mov_b64_e32 v[40:41], 0
	v_mov_b64_e32 v[42:43], 0
	v_mov_b64_e32 v[44:45], 0
	v_mov_b64_e32 v[46:47], 0
	v_mov_b64_e32 v[48:49], 0
	v_mov_b64_e32 v[50:51], 0
	v_mov_b64_e32 v[52:53], 0
	v_mov_b64_e32 v[54:55], 0
	v_mov_b64_e32 v[56:57], 0
	v_mov_b64_e32 v[58:59], 0
	v_mov_b64_e32 v[60:61], 0
	v_mov_b64_e32 v[62:63], 0
	v_mov_b64_e32 v[64:65], 0
	v_mov_b64_e32 v[66:67], 0
	v_mov_b64_e32 v[68:69], 0
	v_mov_b64_e32 v[70:71], 0
	v_mov_b64_e32 v[72:73], 0
	v_mov_b64_e32 v[74:75], 0
	v_mov_b64_e32 v[76:77], 0
	v_mov_b64_e32 v[78:79], 0
	v_mov_b64_e32 v[80:81], 0
	v_mov_b64_e32 v[82:83], 0
	v_mov_b64_e32 v[84:85], 0
	v_mov_b64_e32 v[86:87], 0
	v_mov_b64_e32 v[88:89], 0
	v_mov_b64_e32 v[90:91], 0
	v_mov_b64_e32 v[96:97], 0
	v_mov_b64_e32 v[98:99], 0
	v_mov_b64_e32 v[92:93], 0
	v_mov_b64_e32 v[94:95], 0
	v_mov_b64_e32 v[100:101], 0
	v_mov_b64_e32 v[102:103], 0
	v_mov_b64_e32 v[104:105], 0
	v_mov_b64_e32 v[106:107], 0
	v_mov_b64_e32 v[108:109], 0
	v_mov_b64_e32 v[110:111], 0
	v_mov_b64_e32 v[112:113], 0
	v_mov_b64_e32 v[114:115], 0
	v_mov_b64_e32 v[116:117], 0
	v_mov_b64_e32 v[118:119], 0
	v_mov_b64_e32 v[120:121], 0
	v_mov_b64_e32 v[122:123], 0
	v_mov_b64_e32 v[124:125], 0
	v_mov_b64_e32 v[126:127], 0

; template <class Sched, class Epi>
; DI void gemm_stream(char* smem, const Sched& S_, const Epi& E) {
;     ...
;     const bool has_next = S_.next(ui + 1, nxt);
;     if (!has_next) nxt = cur;
;     const char* nA = nxt.A; const char* nB = nxt.B;
;     const int nt = cur.nt;
;     const int la2 = cur.lda * 2; const size_t hA = (size_t)HALF * la2;
;     for (int t = 0; t < nt; t += 2) {
;       const bool last = (t == nt - 2);
;       const char* a1 = cA + (size_t)(t + 1) * kstep;
;       const char* a2 = last ? nA : cA + (size_t)(t + 2) * kstep; const char* b2 = last ? nB : cB + (size_t)(t + 2) * kstep;
;       const char* a3 = a2 + kstep; const char* b3 = b2 + kstep;
;       const int xa2 = (last ? nxt.lda : cur.lda) * 2, xb2 = (last ? nxt.ldb : cur.ldb) * 2;
;       const size_t xhA = (size_t)HALF * xa2, xhB = (size_t)HALF * xb2;
;     ...
; #pragma unroll
;     for (int a = 0; a < 2; ++a)
; #pragma unroll
;       for (int b = 0; b < 2; ++b)
; #pragma unroll
;         for (int m = 0; m < 4; ++m)
; #pragma unroll
;           for (int n = 0; n < 2; ++n) acc[a][b][m][n] = (f32x4){0.f, 0.f, 0.f, 0.f};
;     cur = nxt; cA = nA; cB = nB; ++ui;
.LBB0_1165:
	s_lshl_b32 s50, s20, 1
	s_ashr_i32 s51, s50, 31
	s_lshl_b64 s[56:57], s[50:51], 7
	s_add_i32 s62, s5, -2
	s_add_u32 s44, s44, 0x80
	s_addc_u32 s45, s45, 0
	s_add_u32 s63, s46, 0x100
	s_addc_u32 s52, s47, 0
	v_mad_u64_u32 v[0:1], s[46:47], s50, v234, v[194:195]
	v_mov_b32_e32 v1, v221
	v_lshl_add_u64 v[128:129], s[56:57], 0, v[0:1]
	v_mad_u64_u32 v[0:1], s[46:47], s50, v235, v[208:209]
	v_mov_b32_e32 v1, v221
	v_lshl_add_u64 v[130:131], s[56:57], 0, v[0:1]
	v_mov_b32_e32 v0, 0
	s_mov_b32 s46, 0
	v_mov_b32_e32 v1, 0
	v_mov_b64_e32 v[2:3], 0
	v_mov_b64_e32 v[4:5], 0
	v_mov_b64_e32 v[6:7], 0
	v_mov_b64_e32 v[8:9], 0
	v_mov_b64_e32 v[10:11], 0
	v_mov_b64_e32 v[12:13], 0
	v_mov_b64_e32 v[14:15], 0
	v_mov_b64_e32 v[24:25], 0
	v_mov_b64_e32 v[26:27], 0
	v_mov_b64_e32 v[28:29], 0
	v_mov_b64_e32 v[30:31], 0
	v_mov_b64_e32 v[40:41], 0
	v_mov_b64_e32 v[42:43], 0
	v_mov_b64_e32 v[44:45], 0
	v_mov_b64_e32 v[46:47], 0
	v_mov_b64_e32 v[16:17], 0
	v_mov_b64_e32 v[18:19], 0
	v_mov_b64_e32 v[20:21], 0
	v_mov_b64_e32 v[22:23], 0
	v_mov_b64_e32 v[32:33], 0
	v_mov_b64_e32 v[34:35], 0
	v_mov_b64_e32 v[36:37], 0
	v_mov_b64_e32 v[38:39], 0
	v_mov_b64_e32 v[48:49], 0
	v_mov_b64_e32 v[50:51], 0
	v_mov_b64_e32 v[52:53], 0
	v_mov_b64_e32 v[54:55], 0
	v_mov_b64_e32 v[56:57], 0
	v_mov_b64_e32 v[58:59], 0
	v_mov_b64_e32 v[60:61], 0
	v_mov_b64_e32 v[62:63], 0
	v_mov_b64_e32 v[64:65], 0
	v_mov_b64_e32 v[66:67], 0
	v_mov_b64_e32 v[68:69], 0
	v_mov_b64_e32 v[70:71], 0
	v_mov_b64_e32 v[72:73], 0
	v_mov_b64_e32 v[74:75], 0
	v_mov_b64_e32 v[76:77], 0
	v_mov_b64_e32 v[78:79], 0
	v_mov_b64_e32 v[88:89], 0
	v_mov_b64_e32 v[90:91], 0
	v_mov_b64_e32 v[92:93], 0
	v_mov_b64_e32 v[94:95], 0
	v_mov_b64_e32 v[104:105], 0
	v_mov_b64_e32 v[106:107], 0
	s_waitcnt vmcnt(0)
	v_mov_b64_e32 v[108:109], 0
	v_mov_b64_e32 v[110:111], 0
	v_mov_b64_e32 v[80:81], 0
	v_mov_b64_e32 v[82:83], 0
	v_mov_b64_e32 v[84:85], 0
	v_mov_b64_e32 v[86:87], 0
	v_mov_b64_e32 v[96:97], 0
	v_mov_b64_e32 v[98:99], 0
	v_mov_b64_e32 v[100:101], 0
	v_mov_b64_e32 v[102:103], 0
	v_mov_b64_e32 v[112:113], 0
	v_mov_b64_e32 v[114:115], 0
	v_mov_b64_e32 v[116:117], 0
	v_mov_b64_e32 v[118:119], 0
	v_mov_b64_e32 v[120:121], 0
	v_mov_b64_e32 v[122:123], 0
	v_mov_b64_e32 v[124:125], 0
	v_mov_b64_e32 v[126:127], 0

; template <class Epi>
; DI void gemm_phase(char* smem, const bf16_t* A, int lda, const bf16_t* Bt, int ldb, int K, const Order& S_, const Epi& E) {
;     ...
;     const bool has_next = S_.next(ui + 1, nxt);
;     const char* nA = has_next ? (const char*)A + (size_t)nxt.pm * tstepA : cA; const char* nB = has_next ? (const char*)Bt + (size_t)nxt.pn * tstepB : cB;
;     for (int t = 0; t < nt; t += 2) {
;       const bool last = (t == nt - 2);
;       const char* a1 = cA + (size_t)(t + 1) * kstep;
;       const char* a2 = last ? nA : cA + (size_t)(t + 2) * kstep; const char* b2 = last ? nB : cB + (size_t)(t + 2) * kstep;
;       const char* a3 = a2 + kstep; const char* b3 = b2 + kstep;
;     ...
; #pragma unroll
;     for (int a = 0; a < 2; ++a)
; #pragma unroll
;       for (int b = 0; b < 2; ++b)
; #pragma unroll
;         for (int m = 0; m < 4; ++m)
; #pragma unroll
;           for (int n = 0; n < 2; ++n) acc[a][b][m][n] = (f32x4){0.f, 0.f, 0.f, 0.f};
;     cur = nxt; cA = nA; cB = nB; ++ui;
.LBB0_1700:
	s_ashr_i32 s41, s40, 31
	s_lshl_b64 s[50:51], s[40:41], 19
	s_add_u32 s88, s9, s50
	s_addc_u32 s89, s13, s51
	s_and_b64 s[0:1], s[0:1], exec
	s_cselect_b32 s5, s89, s47
	s_cselect_b32 s15, s88, s46
	s_add_u32 s16, s46, 0x100
	v_mov_b32_e32 v0, 0
	s_addc_u32 s20, s47, 0
	s_mov_b32 s29, -2
	v_mov_b32_e32 v1, 0
	v_mov_b64_e32 v[2:3], 0
	v_mov_b64_e32 v[4:5], 0
	v_mov_b64_e32 v[6:7], 0
	v_mov_b64_e32 v[8:9], 0
	v_mov_b64_e32 v[10:11], 0
	v_mov_b64_e32 v[16:17], 0
	v_mov_b64_e32 v[18:19], 0
	v_mov_b64_e32 v[32:33], 0
	v_mov_b64_e32 v[34:35], 0
	v_mov_b64_e32 v[36:37], 0
	v_mov_b64_e32 v[38:39], 0
	v_mov_b64_e32 v[40:41], 0
	v_mov_b64_e32 v[42:43], 0
	v_mov_b64_e32 v[48:49], 0
	v_mov_b64_e32 v[50:51], 0
	v_mov_b64_e32 v[12:13], 0
	v_mov_b64_e32 v[14:15], 0
	v_mov_b64_e32 v[20:21], 0
	v_mov_b64_e32 v[22:23], 0
	v_mov_b64_e32 v[24:25], 0
	v_mov_b64_e32 v[26:27], 0
	v_mov_b64_e32 v[28:29], 0
	v_mov_b64_e32 v[30:31], 0
	v_mov_b64_e32 v[44:45], 0
	v_mov_b64_e32 v[46:47], 0
	v_mov_b64_e32 v[52:53], 0
	v_mov_b64_e32 v[54:55], 0
	v_mov_b64_e32 v[56:57], 0
	v_mov_b64_e32 v[58:59], 0
	v_mov_b64_e32 v[60:61], 0
	v_mov_b64_e32 v[62:63], 0
	v_mov_b64_e32 v[80:81], 0
	v_mov_b64_e32 v[82:83], 0
	v_mov_b64_e32 v[84:85], 0
	v_mov_b64_e32 v[86:87], 0
	v_mov_b64_e32 v[88:89], 0
	v_mov_b64_e32 v[90:91], 0
	v_mov_b64_e32 v[96:97], 0
	v_mov_b64_e32 v[98:99], 0
	v_mov_b64_e32 v[112:113], 0
	v_mov_b64_e32 v[114:115], 0
	v_mov_b64_e32 v[116:117], 0
	v_mov_b64_e32 v[118:119], 0
	v_mov_b64_e32 v[120:121], 0
	v_mov_b64_e32 v[122:123], 0
	v_mov_b64_e32 v[128:129], 0
	v_mov_b64_e32 v[130:131], 0
	v_mov_b64_e32 v[92:93], 0
	v_mov_b64_e32 v[94:95], 0
	v_mov_b64_e32 v[100:101], 0
	v_mov_b64_e32 v[102:103], 0
	v_mov_b64_e32 v[104:105], 0
	v_mov_b64_e32 v[106:107], 0
	v_mov_b64_e32 v[108:109], 0
	v_mov_b64_e32 v[110:111], 0
	v_mov_b64_e32 v[124:125], 0
	v_mov_b64_e32 v[126:127], 0
	v_mov_b64_e32 v[132:133], 0
	v_mov_b64_e32 v[134:135], 0
	v_mov_b64_e32 v[136:137], 0
	v_mov_b64_e32 v[138:139], 0
	v_mov_b64_e32 v[140:141], 0
	v_mov_b64_e32 v[142:143], 0

; template <class Epi>
; DI void gemm_phase(char* smem, const bf16_t* A, int lda, const bf16_t* Bt, int ldb, int K, const Order& S_, const Epi& E) {
;     ...
;     const bool has_next = S_.next(ui + 1, nxt);
;     const char* nA = has_next ? (const char*)A + (size_t)nxt.pm * tstepA : cA; const char* nB = has_next ? (const char*)Bt + (size_t)nxt.pn * tstepB : cB;
;     for (int t = 0; t < nt; t += 2) {
;       const bool last = (t == nt - 2);
;       const char* a1 = cA + (size_t)(t + 1) * kstep;
;       const char* a2 = last ? nA : cA + (size_t)(t + 2) * kstep; const char* b2 = last ? nB : cB + (size_t)(t + 2) * kstep;
;       const char* a3 = a2 + kstep; const char* b3 = b2 + kstep;
;     ...
; #pragma unroll
;     for (int a = 0; a < 2; ++a)
; #pragma unroll
;       for (int b = 0; b < 2; ++b)
; #pragma unroll
;         for (int m = 0; m < 4; ++m)
; #pragma unroll
;           for (int n = 0; n < 2; ++n) acc[a][b][m][n] = (f32x4){0.f, 0.f, 0.f, 0.f};
;     cur = nxt; cA = nA; cB = nB; ++ui;
.LBB0_1857:
	v_mov_b64_e32 v[0:1], s[60:61]
	s_ashr_i32 s41, s40, 31
	v_cmp_lt_i64_e32 vcc, s[44:45], v[0:1]
	s_lshl_b64 s[4:5], s[40:41], 19
	v_readlane_b32 s44, v251, 55
	v_readlane_b32 s45, v251, 56
	s_add_u32 s50, s44, s4
	s_addc_u32 s51, s45, s5
	s_and_b64 s[4:5], vcc, exec
	s_cselect_b32 s4, s51, s43
	s_cselect_b32 s5, s50, s42
	s_ashr_i32 s91, s90, 31
	s_lshl_b64 s[44:45], s[90:91], 19
	s_add_u32 s44, s26, s44
	s_addc_u32 s45, s27, s45
	s_and_b64 s[52:53], vcc, exec
	s_cselect_b32 s15, s45, s89
	s_cselect_b32 s16, s44, s88
	s_add_u32 vcc_lo, s42, 0x40080
	s_addc_u32 vcc_hi, s43, 0
	s_add_u32 s20, s88, 0x100
	v_mov_b32_e32 v0, 0
	s_addc_u32 s29, s89, 0
	s_mov_b32 s41, -2
	v_mov_b32_e32 v1, 0
	v_mov_b64_e32 v[2:3], 0
	v_mov_b64_e32 v[8:9], 0
	v_mov_b64_e32 v[10:11], 0
	v_mov_b64_e32 v[16:17], 0
	v_mov_b64_e32 v[18:19], 0
	v_mov_b64_e32 v[24:25], 0
	v_mov_b64_e32 v[26:27], 0
	v_mov_b64_e32 v[32:33], 0
	v_mov_b64_e32 v[34:35], 0
	v_mov_b64_e32 v[40:41], 0
	v_mov_b64_e32 v[42:43], 0
	v_mov_b64_e32 v[48:49], 0
	v_mov_b64_e32 v[50:51], 0
	v_mov_b64_e32 v[56:57], 0
	v_mov_b64_e32 v[58:59], 0
	v_mov_b64_e32 v[4:5], 0
	v_mov_b64_e32 v[6:7], 0
	v_mov_b64_e32 v[12:13], 0
	v_mov_b64_e32 v[14:15], 0
	v_mov_b64_e32 v[20:21], 0
	v_mov_b64_e32 v[22:23], 0
	v_mov_b64_e32 v[28:29], 0
	v_mov_b64_e32 v[30:31], 0
	v_mov_b64_e32 v[36:37], 0
	v_mov_b64_e32 v[38:39], 0
	v_mov_b64_e32 v[44:45], 0
	v_mov_b64_e32 v[46:47], 0
	v_mov_b64_e32 v[52:53], 0
	v_mov_b64_e32 v[54:55], 0
	v_mov_b64_e32 v[60:61], 0
	v_mov_b64_e32 v[62:63], 0
	v_mov_b64_e32 v[64:65], 0
	v_mov_b64_e32 v[66:67], 0
	v_mov_b64_e32 v[72:73], 0
	v_mov_b64_e32 v[74:75], 0
	v_mov_b64_e32 v[80:81], 0
	v_mov_b64_e32 v[82:83], 0
	v_mov_b64_e32 v[88:89], 0
	v_mov_b64_e32 v[90:91], 0
	v_mov_b64_e32 v[96:97], 0
	v_mov_b64_e32 v[98:99], 0
	v_mov_b64_e32 v[104:105], 0
	v_mov_b64_e32 v[106:107], 0
	v_mov_b64_e32 v[112:113], 0
	v_mov_b64_e32 v[114:115], 0
	v_mov_b64_e32 v[120:121], 0
	v_mov_b64_e32 v[122:123], 0
	v_mov_b64_e32 v[68:69], 0
	v_mov_b64_e32 v[70:71], 0
	v_mov_b64_e32 v[76:77], 0
	v_mov_b64_e32 v[78:79], 0
	v_mov_b64_e32 v[84:85], 0
	v_mov_b64_e32 v[86:87], 0
	v_mov_b64_e32 v[92:93], 0
	v_mov_b64_e32 v[94:95], 0
	v_mov_b64_e32 v[100:101], 0
	v_mov_b64_e32 v[102:103], 0
	v_mov_b64_e32 v[108:109], 0
	v_mov_b64_e32 v[110:111], 0
	v_mov_b64_e32 v[116:117], 0
	v_mov_b64_e32 v[118:119], 0
	v_mov_b64_e32 v[124:125], 0
	v_mov_b64_e32 v[126:127], 0

; template <class Epi>
; DI void gemm_phase(char* smem, const bf16_t* A, int lda, const bf16_t* Bt, int ldb, int K, const Order& S_, const Epi& E) {
;     ...
;     const bool has_next = S_.next(ui + 1, nxt);
;     const char* nA = has_next ? (const char*)A + (size_t)nxt.pm * tstepA : cA; const char* nB = has_next ? (const char*)Bt + (size_t)nxt.pn * tstepB : cB;
;     for (int t = 0; t < nt; t += 2) {
;       const bool last = (t == nt - 2);
;       const char* a1 = cA + (size_t)(t + 1) * kstep;
;       const char* a2 = last ? nA : cA + (size_t)(t + 2) * kstep; const char* b2 = last ? nB : cB + (size_t)(t + 2) * kstep;
;       const char* a3 = a2 + kstep; const char* b3 = b2 + kstep;
;     ...
; #pragma unroll
;     for (int a = 0; a < 2; ++a)
; #pragma unroll
;       for (int b = 0; b < 2; ++b)
; #pragma unroll
;         for (int m = 0; m < 4; ++m)
; #pragma unroll
;           for (int n = 0; n < 2; ++n) acc[a][b][m][n] = (f32x4){0.f, 0.f, 0.f, 0.f};
;     cur = nxt; cA = nA; cB = nB; ++ui;
.LBB0_1928:
	s_add_u32 s52, s44, 0x100
	v_mov_b32_e32 v0, 0
	s_addc_u32 s53, s45, 0
	s_mov_b32 s56, -2
	v_mov_b32_e32 v1, 0
	v_mov_b64_e32 v[2:3], 0
	v_mov_b64_e32 v[4:5], 0
	v_mov_b64_e32 v[6:7], 0
	v_mov_b64_e32 v[8:9], 0
	v_mov_b64_e32 v[10:11], 0
	v_mov_b64_e32 v[12:13], 0
	v_mov_b64_e32 v[14:15], 0
	v_mov_b64_e32 v[32:33], 0
	v_mov_b64_e32 v[34:35], 0
	v_mov_b64_e32 v[36:37], 0
	v_mov_b64_e32 v[38:39], 0
	v_mov_b64_e32 v[40:41], 0
	v_mov_b64_e32 v[42:43], 0
	v_mov_b64_e32 v[44:45], 0
	v_mov_b64_e32 v[46:47], 0
	v_mov_b64_e32 v[16:17], 0
	v_mov_b64_e32 v[18:19], 0
	v_mov_b64_e32 v[20:21], 0
	v_mov_b64_e32 v[22:23], 0
	v_mov_b64_e32 v[24:25], 0
	v_mov_b64_e32 v[26:27], 0
	v_mov_b64_e32 v[28:29], 0
	v_mov_b64_e32 v[30:31], 0
	v_mov_b64_e32 v[48:49], 0
	v_mov_b64_e32 v[50:51], 0
	v_mov_b64_e32 v[52:53], 0
	v_mov_b64_e32 v[54:55], 0
	v_mov_b64_e32 v[56:57], 0
	v_mov_b64_e32 v[58:59], 0
	v_mov_b64_e32 v[60:61], 0
	v_mov_b64_e32 v[62:63], 0
	v_mov_b64_e32 v[64:65], 0
	v_mov_b64_e32 v[66:67], 0
	v_mov_b64_e32 v[68:69], 0
	v_mov_b64_e32 v[70:71], 0
	v_mov_b64_e32 v[72:73], 0
	v_mov_b64_e32 v[74:75], 0
	v_mov_b64_e32 v[76:77], 0
	v_mov_b64_e32 v[78:79], 0
	v_mov_b64_e32 v[96:97], 0
	v_mov_b64_e32 v[98:99], 0
	v_mov_b64_e32 v[100:101], 0
	v_mov_b64_e32 v[102:103], 0
	v_mov_b64_e32 v[104:105], 0
	v_mov_b64_e32 v[106:107], 0
	v_mov_b64_e32 v[112:113], 0
	v_mov_b64_e32 v[114:115], 0
	v_mov_b64_e32 v[80:81], 0
	v_mov_b64_e32 v[82:83], 0
	v_mov_b64_e32 v[84:85], 0
	v_mov_b64_e32 v[86:87], 0
	v_mov_b64_e32 v[88:89], 0
	v_mov_b64_e32 v[90:91], 0
	v_mov_b64_e32 v[92:93], 0
	v_mov_b64_e32 v[94:95], 0
	v_mov_b64_e32 v[108:109], 0
	v_mov_b64_e32 v[110:111], 0
	v_mov_b64_e32 v[116:117], 0
	v_mov_b64_e32 v[118:119], 0
	v_mov_b64_e32 v[120:121], 0
	v_mov_b64_e32 v[122:123], 0
	v_mov_b64_e32 v[124:125], 0
	v_mov_b64_e32 v[126:127], 0
